# rwkv_pre_wave: LDS reads of the T-inverse block products and the back substitution issued in batches (about 170 serialized LDS round trips removed per item)
# speedup vs baseline: 1.0077x; 1.0077x over previous
.LBB0_799:
	s_or_b64 exec, exec, s[0:1]
	s_mov_b64 s[0:1], 0x4400
	v_lshl_add_u64 v[74:75], v[110:111], 0, s[0:1]
	s_mov_b64 s[0:1], 0x4800
	v_lshl_add_u64 v[62:63], v[110:111], 0, s[0:1]
	s_mov_b64 s[0:1], 0x4c00
	v_lshl_add_u64 v[60:61], v[110:111], 0, s[0:1]
	v_cmp_gt_i32_e64 s[0:1], v108, v107
	v_cmp_gt_i32_e64 s[2:3], v149, v107
	v_cmp_gt_i32_e64 s[26:27], v151, v107
	v_cndmask_b32_e64 v53, 0, v32, s[0:1]
	v_cndmask_b32_e64 v99, v18, 0, s[2:3]
	v_cndmask_b32_e64 v105, 0, v46, s[26:27]
	v_cndmask_b32_e64 v46, v16, 0, s[0:1]
	v_cndmask_b32_e64 v0, v0, 0, s[0:1]
	v_ashrrev_i32_e32 v51, 2, v136
	s_movk_i32 s0, 0x84
	v_lshlrev_b32_e32 v18, 2, v96
	s_waitcnt lgkmcnt(0)
	v_mul_lo_u32 v16, v51, s0
	v_and_b32_e32 v50, 48, v18
	v_cmp_gt_i32_e64 s[10:11], v147, v107
	v_cmp_gt_i32_e64 s[12:13], v146, v107
	v_cmp_gt_i32_e64 s[30:31], v152, v107
	v_add_u32_e32 v49, s76, v16
	v_add_u32_e32 v48, s76, v50
	v_cndmask_b32_e64 v138, 0, v47, s[30:31]
	v_cndmask_b32_e32 v47, 0, v17, vcc
	v_cndmask_b32_e64 v104, v22, 0, s[10:11]
	v_cndmask_b32_e64 v109, v23, 0, s[12:13]
	ds_read2_b32 v[16:17], v49 offset0:16 offset1:17
	ds_read_b64 v[22:23], v48 offset:6400
	v_cmp_gt_i32_e64 s[14:15], v140, v107
	v_cmp_gt_i32_e64 s[16:17], v139, v107
	v_cndmask_b32_e64 v87, v30, 0, s[26:27]
	v_cndmask_b32_e64 v78, v24, 0, s[14:15]
	s_waitcnt lgkmcnt(0)
	v_fma_f32 v22, v16, v22, 0
	v_add_u32_e32 v16, 0x1984, v48
	v_cndmask_b32_e64 v79, v25, 0, s[16:17]
	ds_read2_b32 v[24:25], v16 offset1:1
	v_cndmask_b32_e64 v89, v31, 0, s[30:31]
	v_cndmask_b32_e64 v54, v33, 0, vcc
	v_cndmask_b32_e64 v91, 0, v38, s[10:11]
	v_cndmask_b32_e64 v94, 0, v39, s[12:13]
	s_waitcnt lgkmcnt(0)
	v_fmac_f32_e32 v22, v17, v24
	ds_read2_b32 v[16:17], v49 offset0:18 offset1:19
	ds_read_b64 v[30:31], v48 offset:6664
	v_cndmask_b32_e64 v88, 0, v40, s[14:15]
	v_cndmask_b32_e64 v92, 0, v41, s[16:17]
	v_cmp_gt_i32_e64 s[18:19], v145, v107
	v_cmp_gt_i32_e64 s[20:21], v144, v107
	s_waitcnt lgkmcnt(0)
	v_fmac_f32_e32 v22, v16, v30
	v_add_u32_e32 v16, 0x1a8c, v48
	ds_read2_b32 v[32:33], v16 offset1:1
	v_cndmask_b32_e64 v93, 0, v42, s[18:19]
	v_cndmask_b32_e64 v95, 0, v43, s[20:21]
	v_cmp_gt_i32_e64 s[22:23], v143, v107
	v_cmp_gt_i32_e64 s[24:25], v150, v107
	s_waitcnt lgkmcnt(0)
	v_fmac_f32_e32 v22, v17, v32
	ds_read2_b32 v[16:17], v49 offset0:20 offset1:21
	ds_read_b64 v[38:39], v48 offset:6928
	v_cndmask_b32_e64 v98, 0, v44, s[22:23]
	v_cndmask_b32_e64 v102, 0, v45, s[24:25]
	v_cmp_gt_i32_e64 s[4:5], v148, v107
	v_cndmask_b32_e64 v55, 0, v34, s[2:3]
	s_waitcnt lgkmcnt(0)
	v_fmac_f32_e32 v22, v16, v38
	v_add_u32_e32 v16, 0x1b94, v48
	ds_read2_b32 v[40:41], v16 offset1:1
	v_cndmask_b32_e64 v81, 0, v35, s[4:5]
	v_lshl_add_u64 v[76:77], v[110:111], 0, s[6:7]
	v_cmp_gt_i32_e64 s[6:7], v141, v107
	v_cmp_gt_i32_e64 s[8:9], v142, v107
	s_waitcnt lgkmcnt(0)
	v_fmac_f32_e32 v22, v17, v40
	ds_read2_b32 v[16:17], v49 offset0:22 offset1:23
	ds_read_b64 v[42:43], v48 offset:7192
	v_cndmask_b32_e64 v85, 0, v36, s[6:7]
	v_cndmask_b32_e64 v90, 0, v37, s[8:9]
	v_cndmask_b32_e64 v80, v26, 0, s[18:19]
	v_cndmask_b32_e64 v82, v27, 0, s[20:21]
	s_waitcnt lgkmcnt(0)
	v_fmac_f32_e32 v22, v16, v42
	v_add_u32_e32 v16, 0x1c9c, v48
	ds_read2_b32 v[44:45], v16 offset1:1
	v_cndmask_b32_e64 v83, v28, 0, s[22:23]
	v_cndmask_b32_e64 v86, v29, 0, s[24:25]
	v_cndmask_b32_e64 v100, v19, 0, s[4:5]
	v_cndmask_b32_e64 v101, v20, 0, s[6:7]
	s_waitcnt lgkmcnt(0)
	v_fmac_f32_e32 v22, v17, v44
	ds_read2_b32 v[16:17], v49 offset0:24 offset1:25
	ds_read_b64 v[34:35], v48 offset:7456
	v_cndmask_b32_e64 v103, v21, 0, s[8:9]
	v_cndmask_b32_e64 v15, v15, 0, s[30:31]
	v_cndmask_b32_e32 v1, 0, v1, vcc
	v_cndmask_b32_e64 v2, v2, 0, s[2:3]
	s_waitcnt lgkmcnt(0)
	v_fmac_f32_e32 v22, v16, v34
	v_add_u32_e32 v16, 0x1da4, v48
	ds_read2_b32 v[36:37], v16 offset1:1
	v_cndmask_b32_e64 v3, v3, 0, s[4:5]
	v_cndmask_b32_e64 v4, v4, 0, s[6:7]
	v_cndmask_b32_e64 v5, v5, 0, s[8:9]
	v_cndmask_b32_e64 v6, v6, 0, s[10:11]
	s_waitcnt lgkmcnt(0)
	v_fmac_f32_e32 v22, v17, v36
	ds_read2_b32 v[16:17], v49 offset0:26 offset1:27
	ds_read_b64 v[26:27], v48 offset:7720
	v_cndmask_b32_e64 v7, v7, 0, s[12:13]
	v_cndmask_b32_e64 v8, v8, 0, s[14:15]
	v_cndmask_b32_e64 v9, v9, 0, s[16:17]
	v_cndmask_b32_e64 v10, v10, 0, s[18:19]
	s_waitcnt lgkmcnt(0)
	v_fmac_f32_e32 v22, v16, v26
	v_add_u32_e32 v16, 0x1eac, v48
	ds_read2_b32 v[28:29], v16 offset1:1
	v_cndmask_b32_e64 v11, v11, 0, s[20:21]
	v_cndmask_b32_e64 v12, v12, 0, s[22:23]
	v_cndmask_b32_e64 v13, v13, 0, s[24:25]
	v_cndmask_b32_e64 v14, v14, 0, s[26:27]
	s_waitcnt lgkmcnt(0)
	v_fmac_f32_e32 v22, v17, v28
	ds_read2_b32 v[16:17], v49 offset0:28 offset1:29
	ds_read_b64 v[18:19], v48 offset:7984
	s_waitcnt lgkmcnt(0)
	v_fmac_f32_e32 v22, v16, v18
	v_add_u32_e32 v16, 0x1fb4, v48
	ds_read2_b32 v[20:21], v16 offset1:1
	s_waitcnt lgkmcnt(0)
	v_fmac_f32_e32 v22, v17, v20
	ds_read2_b32 v[56:57], v49 offset0:30 offset1:31
	ds_read_b64 v[16:17], v48 offset:8248
	s_waitcnt lgkmcnt(0)
	v_fmac_f32_e32 v22, v56, v16
	ds_read_b32 v16, v48 offset:8380
	s_waitcnt lgkmcnt(0)
	v_fmac_f32_e32 v22, v57, v16
	v_lshl_add_u32 v16, v51, 6, v48
	ds_write_b32 v16, v22 offset:8448
	ds_read2_b32 v[192:193], v49 offset0:16 offset1:17
	ds_read2_b32 v[194:195], v49 offset0:18 offset1:19
	ds_read2_b32 v[196:197], v49 offset0:20 offset1:21
	ds_read2_b32 v[198:199], v49 offset0:22 offset1:23
	ds_read2_b32 v[200:201], v49 offset0:24 offset1:25
	ds_read2_b32 v[202:203], v49 offset0:26 offset1:27
	ds_read2_b32 v[204:205], v49 offset0:28 offset1:29
	ds_read2_b32 v[206:207], v49 offset0:30 offset1:31
	v_lshl_add_u32 v236, v51, 6, v48
	ds_read_b32 v208, v48 offset:6404
	ds_read_b32 v209, v48 offset:6536
	ds_read_b32 v210, v48 offset:6668
	ds_read_b32 v211, v48 offset:6800
	ds_read_b32 v212, v48 offset:6932
	ds_read_b32 v213, v48 offset:7064
	ds_read_b32 v222, v48 offset:7196
	ds_read_b32 v223, v48 offset:7328
	ds_read_b32 v224, v48 offset:7460
	ds_read_b32 v225, v48 offset:7592
	ds_read_b32 v226, v48 offset:7724
	ds_read_b32 v227, v48 offset:7856
	ds_read_b32 v228, v48 offset:7988
	ds_read_b32 v229, v48 offset:8120
	ds_read_b32 v233, v48 offset:8252
	ds_read_b32 v234, v48 offset:8384
	s_waitcnt lgkmcnt(0)
	v_fma_f32 v235, v192, v208, 0
	v_fmac_f32_e32 v235, v193, v209
	v_fmac_f32_e32 v235, v194, v210
	v_fmac_f32_e32 v235, v195, v211
	v_fmac_f32_e32 v235, v196, v212
	v_fmac_f32_e32 v235, v197, v213
	v_fmac_f32_e32 v235, v198, v222
	v_fmac_f32_e32 v235, v199, v223
	v_fmac_f32_e32 v235, v200, v224
	v_fmac_f32_e32 v235, v201, v225
	v_fmac_f32_e32 v235, v202, v226
	v_fmac_f32_e32 v235, v203, v227
	v_fmac_f32_e32 v235, v204, v228
	v_fmac_f32_e32 v235, v205, v229
	v_fmac_f32_e32 v235, v206, v233
	v_fmac_f32_e32 v235, v207, v234
	ds_write_b32 v236, v235 offset:8452
	ds_read_b32 v208, v48 offset:6408
	ds_read_b32 v209, v48 offset:6540
	ds_read_b32 v210, v48 offset:6672
	ds_read_b32 v211, v48 offset:6804
	ds_read_b32 v212, v48 offset:6936
	ds_read_b32 v213, v48 offset:7068
	ds_read_b32 v222, v48 offset:7200
	ds_read_b32 v223, v48 offset:7332
	ds_read_b32 v224, v48 offset:7464
	ds_read_b32 v225, v48 offset:7596
	ds_read_b32 v226, v48 offset:7728
	ds_read_b32 v227, v48 offset:7860
	ds_read_b32 v228, v48 offset:7992
	ds_read_b32 v229, v48 offset:8124
	ds_read_b32 v233, v48 offset:8256
	ds_read_b32 v234, v48 offset:8388
	s_waitcnt lgkmcnt(0)
	v_fma_f32 v238, v192, v208, 0
	v_fmac_f32_e32 v238, v193, v209
	v_fmac_f32_e32 v238, v194, v210
	v_fmac_f32_e32 v238, v195, v211
	v_fmac_f32_e32 v238, v196, v212
	v_fmac_f32_e32 v238, v197, v213
	v_fmac_f32_e32 v238, v198, v222
	v_fmac_f32_e32 v238, v199, v223
	v_fmac_f32_e32 v238, v200, v224
	v_fmac_f32_e32 v238, v201, v225
	v_fmac_f32_e32 v238, v202, v226
	v_fmac_f32_e32 v238, v203, v227
	v_fmac_f32_e32 v238, v204, v228
	v_fmac_f32_e32 v238, v205, v229
	v_fmac_f32_e32 v238, v206, v233
	v_fmac_f32_e32 v238, v207, v234
	ds_write_b32 v236, v238 offset:8456
	ds_read_b32 v208, v48 offset:6412
	ds_read_b32 v209, v48 offset:6544
	ds_read_b32 v210, v48 offset:6676
	ds_read_b32 v211, v48 offset:6808
	ds_read_b32 v212, v48 offset:6940
	ds_read_b32 v213, v48 offset:7072
	ds_read_b32 v222, v48 offset:7204
	ds_read_b32 v223, v48 offset:7336
	ds_read_b32 v224, v48 offset:7468
	ds_read_b32 v225, v48 offset:7600
	ds_read_b32 v226, v48 offset:7732
	ds_read_b32 v227, v48 offset:7864
	ds_read_b32 v228, v48 offset:7996
	ds_read_b32 v229, v48 offset:8128
	ds_read_b32 v233, v48 offset:8260
	ds_read_b32 v234, v48 offset:8392
	s_waitcnt lgkmcnt(0)
	v_fma_f32 v235, v192, v208, 0
	v_fmac_f32_e32 v235, v193, v209
	v_fmac_f32_e32 v235, v194, v210
	v_fmac_f32_e32 v235, v195, v211
	v_fmac_f32_e32 v235, v196, v212
	v_fmac_f32_e32 v235, v197, v213
	v_fmac_f32_e32 v235, v198, v222
	v_fmac_f32_e32 v235, v199, v223
	v_fmac_f32_e32 v235, v200, v224
	v_fmac_f32_e32 v235, v201, v225
	v_fmac_f32_e32 v235, v202, v226
	v_fmac_f32_e32 v235, v203, v227
	v_fmac_f32_e32 v235, v204, v228
	v_fmac_f32_e32 v235, v205, v229
	v_fmac_f32_e32 v235, v206, v233
	v_fmac_f32_e32 v235, v207, v234
	ds_write_b32 v236, v235 offset:8460
	s_waitcnt lgkmcnt(0)
	v_add_u32_e32 v236, 0x1080, v49
	ds_read2_b32 v[192:193], v236 offset1:1
	ds_read2_b32 v[194:195], v236 offset0:2 offset1:3
	ds_read2_b32 v[196:197], v236 offset0:4 offset1:5
	ds_read2_b32 v[198:199], v236 offset0:6 offset1:7
	ds_read2_b32 v[200:201], v236 offset0:8 offset1:9
	ds_read2_b32 v[202:203], v236 offset0:10 offset1:11
	ds_read2_b32 v[204:205], v236 offset0:12 offset1:13
	ds_read2_b32 v[206:207], v236 offset0:14 offset1:15
	v_add_u32_e32 v239, v49, v50
	ds_read_b32 v208, v48 offset:8448
	ds_read_b32 v209, v48 offset:8512
	ds_read_b32 v210, v48 offset:8576
	ds_read_b32 v211, v48 offset:8640
	ds_read_b32 v212, v48 offset:8704
	ds_read_b32 v213, v48 offset:8768
	ds_read_b32 v222, v48 offset:8832
	ds_read_b32 v223, v48 offset:8896
	ds_read_b32 v224, v48 offset:8960
	ds_read_b32 v225, v48 offset:9024
	ds_read_b32 v226, v48 offset:9088
	ds_read_b32 v227, v48 offset:9152
	ds_read_b32 v228, v48 offset:9216
	ds_read_b32 v229, v48 offset:9280
	ds_read_b32 v233, v48 offset:9344
	ds_read_b32 v234, v48 offset:9408
	s_waitcnt lgkmcnt(0)
	v_fma_f32 v238, -v192, v208, 0
	v_fma_f32 v238, -v193, v209, v238
	v_fma_f32 v238, -v194, v210, v238
	v_fma_f32 v238, -v195, v211, v238
	v_fma_f32 v238, -v196, v212, v238
	v_fma_f32 v238, -v197, v213, v238
	v_fma_f32 v238, -v198, v222, v238
	v_fma_f32 v238, -v199, v223, v238
	v_fma_f32 v238, -v200, v224, v238
	v_fma_f32 v238, -v201, v225, v238
	v_fma_f32 v238, -v202, v226, v238
	v_fma_f32 v238, -v203, v227, v238
	v_fma_f32 v238, -v204, v228, v238
	v_fma_f32 v238, -v205, v229, v238
	v_fma_f32 v238, -v206, v233, v238
	v_fma_f32 v238, -v207, v234, v238
	ds_write_b32 v239, v238 offset:4288
	ds_read_b32 v208, v48 offset:8452
	ds_read_b32 v209, v48 offset:8516
	ds_read_b32 v210, v48 offset:8580
	ds_read_b32 v211, v48 offset:8644
	ds_read_b32 v212, v48 offset:8708
	ds_read_b32 v213, v48 offset:8772
	ds_read_b32 v222, v48 offset:8836
	ds_read_b32 v223, v48 offset:8900
	ds_read_b32 v224, v48 offset:8964
	ds_read_b32 v225, v48 offset:9028
	ds_read_b32 v226, v48 offset:9092
	ds_read_b32 v227, v48 offset:9156
	ds_read_b32 v228, v48 offset:9220
	ds_read_b32 v229, v48 offset:9284
	ds_read_b32 v233, v48 offset:9348
	ds_read_b32 v234, v48 offset:9412
	s_waitcnt lgkmcnt(0)
	v_fma_f32 v235, -v192, v208, 0
	v_fma_f32 v235, -v193, v209, v235
	v_fma_f32 v235, -v194, v210, v235
	v_fma_f32 v235, -v195, v211, v235
	v_fma_f32 v235, -v196, v212, v235
	v_fma_f32 v235, -v197, v213, v235
	v_fma_f32 v235, -v198, v222, v235
	v_fma_f32 v235, -v199, v223, v235
	v_fma_f32 v235, -v200, v224, v235
	v_fma_f32 v235, -v201, v225, v235
	v_fma_f32 v235, -v202, v226, v235
	v_fma_f32 v235, -v203, v227, v235
	v_fma_f32 v235, -v204, v228, v235
	v_fma_f32 v235, -v205, v229, v235
	v_fma_f32 v235, -v206, v233, v235
	v_fma_f32 v235, -v207, v234, v235
	ds_write_b32 v239, v235 offset:4292
	ds_read_b32 v208, v48 offset:8456
	ds_read_b32 v209, v48 offset:8520
	ds_read_b32 v210, v48 offset:8584
	ds_read_b32 v211, v48 offset:8648
	ds_read_b32 v212, v48 offset:8712
	ds_read_b32 v213, v48 offset:8776
	ds_read_b32 v222, v48 offset:8840
	ds_read_b32 v223, v48 offset:8904
	ds_read_b32 v224, v48 offset:8968
	ds_read_b32 v225, v48 offset:9032
	ds_read_b32 v226, v48 offset:9096
	ds_read_b32 v227, v48 offset:9160
	ds_read_b32 v228, v48 offset:9224
	ds_read_b32 v229, v48 offset:9288
	ds_read_b32 v233, v48 offset:9352
	ds_read_b32 v234, v48 offset:9416
	s_waitcnt lgkmcnt(0)
	v_fma_f32 v238, -v192, v208, 0
	v_fma_f32 v238, -v193, v209, v238
	v_fma_f32 v238, -v194, v210, v238
	v_fma_f32 v238, -v195, v211, v238
	v_fma_f32 v238, -v196, v212, v238
	v_fma_f32 v238, -v197, v213, v238
	v_fma_f32 v238, -v198, v222, v238
	v_fma_f32 v238, -v199, v223, v238
	v_fma_f32 v238, -v200, v224, v238
	v_fma_f32 v238, -v201, v225, v238
	v_fma_f32 v238, -v202, v226, v238
	v_fma_f32 v238, -v203, v227, v238
	v_fma_f32 v238, -v204, v228, v238
	v_fma_f32 v238, -v205, v229, v238
	v_fma_f32 v238, -v206, v233, v238
	v_fma_f32 v238, -v207, v234, v238
	ds_write_b32 v239, v238 offset:4296
	ds_read_b32 v208, v48 offset:8460
	ds_read_b32 v209, v48 offset:8524
	ds_read_b32 v210, v48 offset:8588
	ds_read_b32 v211, v48 offset:8652
	ds_read_b32 v212, v48 offset:8716
	ds_read_b32 v213, v48 offset:8780
	ds_read_b32 v222, v48 offset:8844
	ds_read_b32 v223, v48 offset:8908
	ds_read_b32 v224, v48 offset:8972
	ds_read_b32 v225, v48 offset:9036
	ds_read_b32 v226, v48 offset:9100
	ds_read_b32 v227, v48 offset:9164
	ds_read_b32 v228, v48 offset:9228
	ds_read_b32 v229, v48 offset:9292
	ds_read_b32 v233, v48 offset:9356
	ds_read_b32 v234, v48 offset:9420
	s_waitcnt lgkmcnt(0)
	v_fma_f32 v235, -v192, v208, 0
	v_fma_f32 v235, -v193, v209, v235
	v_fma_f32 v235, -v194, v210, v235
	v_fma_f32 v235, -v195, v211, v235
	v_fma_f32 v235, -v196, v212, v235
	v_fma_f32 v235, -v197, v213, v235
	v_fma_f32 v235, -v198, v222, v235
	v_fma_f32 v235, -v199, v223, v235
	v_fma_f32 v235, -v200, v224, v235
	v_fma_f32 v235, -v201, v225, v235
	v_fma_f32 v235, -v202, v226, v235
	v_fma_f32 v235, -v203, v227, v235
	v_fma_f32 v235, -v204, v228, v235
	v_fma_f32 v235, -v205, v229, v235
	v_fma_f32 v235, -v206, v233, v235
	v_fma_f32 v235, -v207, v234, v235
	ds_write_b32 v239, v235 offset:4300
	v_add_u32_e32 v20, 0x1100, v73
	v_add_u32_e32 v26, 0x1000, v52
	s_waitcnt lgkmcnt(0)
	v_mul_u32_u24_e32 v16, 0x84, v107
	v_lshlrev_b32_e32 v17, 2, v108
	v_add3_u32 v31, s76, v16, v17
	ds_read_b32 v30, v84 offset:4224
	v_add_u32_e32 v18, 0x1080, v31
	v_add_u32_e32 v16, 0x1000, v73
	v_add_u32_e32 v22, 0x1088, v31
	ds_read2_b32 v[16:17], v16 offset0:32 offset1:65
	ds_read2_b32 v[18:19], v18 offset1:1
	ds_read2_b32 v[20:21], v20 offset0:34 offset1:199
	ds_read2_b32 v[22:23], v22 offset1:1
	v_add_u32_e32 v24, 0x10a0, v31
	v_add_u32_e32 v28, 0x10a8, v31
	ds_read_b32 v32, v73 offset:5280
	ds_read2_b32 v[24:25], v24 offset1:1
	ds_read2_b32 v[26:27], v26 offset0:32 offset1:65
	ds_read2_b32 v[28:29], v28 offset1:1
	s_waitcnt lgkmcnt(7)
	v_cvt_pk_bf16_f32 v48, v30, v16
	s_waitcnt lgkmcnt(5)
	v_cvt_pk_bf16_f32 v49, v17, v20
	v_mad_u64_u32 v[16:17], s[0:1], v139, s0, v[72:73]
	v_add_u32_e32 v20, 0x10c0, v31
	v_add_u32_e32 v17, 0x1000, v16
	s_waitcnt lgkmcnt(3)
	v_cvt_pk_bf16_f32 v50, v21, v32
	s_waitcnt lgkmcnt(1)
	v_cvt_pk_bf16_f32 v51, v26, v27
	v_cvt_pk_bf16_f32 v32, v18, v19
	v_cvt_pk_bf16_f32 v33, v22, v23
	v_cvt_pk_bf16_f32 v34, v24, v25
	ds_read_b32 v30, v52 offset:5016
	s_waitcnt lgkmcnt(1)
	v_cvt_pk_bf16_f32 v35, v28, v29
	ds_read2_b32 v[18:19], v17 offset0:32 offset1:65
	ds_read2_b32 v[20:21], v20 offset1:1
	v_add_u32_e32 v17, 0x10c8, v31
	v_add_u32_e32 v22, 0x1600, v52
	v_add_u32_e32 v24, 0x10e0, v31
	v_add_u32_e32 v26, 0x1800, v52
	v_add_u32_e32 v28, 0x10e8, v31
	ds_read_b32 v36, v16 offset:4488
	ds_read2_b32 v[16:17], v17 offset1:1
	ds_read2_b32 v[22:23], v22 offset0:110 offset1:143
	ds_read2_b32 v[24:25], v24 offset1:1
	ds_read2_b32 v[28:29], v28 offset1:1
	ds_read2_b32 v[26:27], v26 offset0:48 offset1:81
	s_waitcnt lgkmcnt(0)
	s_waitcnt lgkmcnt(7)
	v_cvt_pk_bf16_f32 v56, v30, v18
	s_waitcnt lgkmcnt(5)
	v_cvt_pk_bf16_f32 v57, v19, v36
	s_waitcnt lgkmcnt(3)
	v_cvt_pk_bf16_f32 v58, v22, v23
	s_waitcnt lgkmcnt(0)
	v_cvt_pk_bf16_f32 v59, v26, v27
	v_cvt_pk_bf16_f32 v140, v20, v21
	v_cvt_pk_bf16_f32 v141, v16, v17
	v_cvt_pk_bf16_f32 v142, v24, v25
	v_cvt_pk_bf16_f32 v143, v28, v29
	v_cvt_pk_bf16_f32 v16, v53, v54
	v_cvt_pk_bf16_f32 v17, v55, v81
	v_cvt_pk_bf16_f32 v18, v85, v90
	v_cvt_pk_bf16_f32 v19, v91, v94
	v_cvt_pk_bf16_f32 v36, v88, v92
	v_cvt_pk_bf16_f32 v37, v93, v95
	v_mfma_f32_32x32x16_bf16 v[16:31], v[48:51], v[16:19], 0
	v_cvt_pk_bf16_f32 v38, v98, v102
	v_cvt_pk_bf16_f32 v39, v105, v138
	v_cvt_pk_bf16_f32 v52, v46, v47
	v_cvt_pk_bf16_f32 v53, v99, v100
	v_cvt_pk_bf16_f32 v54, v101, v103
	v_cvt_pk_bf16_f32 v55, v104, v109
	v_cvt_pk_bf16_f32 v78, v78, v79
	v_mfma_f32_32x32x16_bf16 v[16:31], v[56:59], v[36:39], v[16:31]
	v_cvt_pk_bf16_f32 v79, v80, v82
	v_cvt_pk_bf16_f32 v80, v83, v86
	v_cvt_pk_bf16_f32 v81, v87, v89
	v_mfma_f32_32x32x16_bf16 v[32:47], v[32:35], v[52:55], 0
	s_nop 0
	v_mfma_f32_32x32x16_bf16 v[32:47], v[140:143], v[78:81], v[32:47]
	s_nop 5
	v_xor_b32_e32 v18, 0x80000000, v18
	v_xor_b32_e32 v19, 0x80000000, v19
	v_xor_b32_e32 v20, 0x80000000, v20
	v_xor_b32_e32 v21, 0x80000000, v21
	v_xor_b32_e32 v22, 0x80000000, v22
	v_xor_b32_e32 v23, 0x80000000, v23
	v_xor_b32_e32 v17, 0x80000000, v17
	v_xor_b32_e32 v16, 0x80000000, v16
	v_xor_b32_e32 v84, 0x80000000, v38
	v_xor_b32_e32 v85, 0x80000000, v39
	v_xor_b32_e32 v86, 0x80000000, v40
	v_xor_b32_e32 v87, 0x80000000, v41
	v_cvt_pk_bf16_f32 v38, v16, v17
	v_cvt_pk_bf16_f32 v39, v18, v19
	v_cvt_pk_bf16_f32 v40, v20, v21
	v_cvt_pk_bf16_f32 v41, v22, v23
	v_xor_b32_e32 v24, 0x80000000, v24
	v_xor_b32_e32 v25, 0x80000000, v25
	v_mfma_f32_32x32x16_bf16 v[0:15], v[38:41], v[52:55], v[0:15]
	v_xor_b32_e32 v26, 0x80000000, v26
	v_xor_b32_e32 v27, 0x80000000, v27
	v_xor_b32_e32 v28, 0x80000000, v28
	v_xor_b32_e32 v29, 0x80000000, v29
	v_xor_b32_e32 v30, 0x80000000, v30
	v_xor_b32_e32 v31, 0x80000000, v31
	v_xor_b32_e32 v72, 0x80000000, v34
	v_xor_b32_e32 v73, 0x80000000, v35
	v_xor_b32_e32 v82, 0x80000000, v36
	v_xor_b32_e32 v83, 0x80000000, v37
	v_cvt_pk_bf16_f32 v34, v24, v25
	v_cvt_pk_bf16_f32 v35, v26, v27
	v_cvt_pk_bf16_f32 v36, v28, v29
	v_cvt_pk_bf16_f32 v37, v30, v31
	s_add_u32 s0, s62, 0x2000
	s_addc_u32 s1, s63, 0
	v_mfma_f32_32x32x16_bf16 v[0:15], v[34:37], v[78:81], v[0:15]
	v_xor_b32_e32 v88, 0x80000000, v42
	v_xor_b32_e32 v89, 0x80000000, v43
	v_xor_b32_e32 v90, 0x80000000, v44
	v_xor_b32_e32 v91, 0x80000000, v45
	v_xor_b32_e32 v46, 0x80000000, v46
	v_xor_b32_e32 v47, 0x80000000, v47
	v_xor_b32_e32 v16, 0x80000000, v33
	s_nop 4
	v_cvt_pk_bf16_f32 v0, v0, v1
	v_cvt_pk_bf16_f32 v1, v2, v3
	v_cvt_pk_bf16_f32 v2, v4, v5
	v_cvt_pk_bf16_f32 v3, v6, v7
	v_lshl_add_u64 v[4:5], s[0:1], 0, v[112:113]
	v_xor_b32_e32 v17, 0x80000000, v32
	global_store_dwordx4 v[4:5], v[0:3], off
	v_lshl_add_u64 v[4:5], s[0:1], 0, v[116:117]
	v_cvt_pk_bf16_f32 v42, v17, v16
	v_cvt_pk_bf16_f32 v0, v8, v9
	v_cvt_pk_bf16_f32 v1, v10, v11
	v_cvt_pk_bf16_f32 v2, v12, v13
	v_cvt_pk_bf16_f32 v3, v14, v15
	v_cvt_pk_bf16_f32 v43, v72, v73
	v_cvt_pk_bf16_f32 v44, v82, v83
	v_cvt_pk_bf16_f32 v45, v84, v85
	v_cvt_pk_bf16_f32 v52, v86, v87
	v_cvt_pk_bf16_f32 v53, v88, v89
	v_cvt_pk_bf16_f32 v54, v90, v91
	v_cvt_pk_bf16_f32 v55, v46, v47
	global_store_dwordx4 v[4:5], v[0:3], off
	global_load_dwordx4 v[16:19], v[110:111], off
	global_load_dwordx4 v[20:23], v[110:111], off offset:1024
	s_add_u32 s2, s62, 0x3000
	s_addc_u32 s3, s63, 0
	s_add_u32 s0, s62, 0x1000
	s_addc_u32 s1, s63, 0
	s_waitcnt vmcnt(1)
	v_mfma_f32_32x32x16_bf16 v[0:15], v[16:19], v[48:51], 0
	s_waitcnt vmcnt(0)
	v_mfma_f32_32x32x16_bf16 v[0:15], v[20:23], v[56:59], v[0:15]
	s_nop 11
	v_cvt_pk_bf16_f32 v0, v0, v1
	v_cvt_pk_bf16_f32 v1, v2, v3
	v_cvt_pk_bf16_f32 v2, v4, v5
	v_cvt_pk_bf16_f32 v3, v6, v7
	v_lshl_add_u64 v[4:5], s[2:3], 0, v[112:113]
	global_store_dwordx4 v[4:5], v[0:3], off
	v_lshl_add_u64 v[4:5], s[2:3], 0, v[116:117]
	s_nop 0
	v_cvt_pk_bf16_f32 v0, v8, v9
	v_cvt_pk_bf16_f32 v1, v10, v11
	v_cvt_pk_bf16_f32 v2, v12, v13
	v_cvt_pk_bf16_f32 v3, v14, v15
	global_store_dwordx4 v[4:5], v[0:3], off
	global_load_dwordx4 v[0:3], v[132:133], off
	s_nop 0
	global_load_dwordx4 v[24:27], v[134:135], off
	s_waitcnt vmcnt(1)
	v_mfma_f32_32x32x16_bf16 v[0:15], v[68:71], v[0:3], 0
	s_waitcnt vmcnt(0)
	v_mfma_f32_32x32x16_bf16 v[0:15], v[64:67], v[24:27], v[0:15]
	v_mfma_f32_32x32x16_bf16 v[0:15], v[42:45], v[16:19], v[0:15]
	v_mfma_f32_32x32x16_bf16 v[0:15], v[52:55], v[20:23], v[0:15]
	global_load_dwordx4 v[16:19], v[76:77], off
	s_nop 0
	global_load_dwordx4 v[72:75], v[74:75], off
	s_waitcnt vmcnt(1)
	v_mfma_f32_32x32x16_bf16 v[16:31], v[68:71], v[16:19], 0
	s_waitcnt vmcnt(0)
	v_mfma_f32_32x32x16_bf16 v[16:31], v[64:67], v[72:75], v[16:31]
	global_load_dwordx4 v[72:75], v[114:115], off
	s_waitcnt vmcnt(0)
	v_mfma_f32_32x32x16_bf16 v[16:31], v[38:41], v[72:75], v[16:31]
	global_load_dwordx4 v[72:75], v[118:119], off
	s_waitcnt vmcnt(0)
	v_mfma_f32_32x32x16_bf16 v[16:31], v[34:37], v[72:75], v[16:31]
	s_nop 11
	v_cvt_pk_bf16_f32 v16, v16, v17
	v_cvt_pk_bf16_f32 v17, v18, v19
	v_cvt_pk_bf16_f32 v18, v20, v21
	v_cvt_pk_bf16_f32 v19, v22, v23
	v_lshl_add_u64 v[20:21], s[0:1], 0, v[112:113]
	global_store_dwordx4 v[20:21], v[16:19], off
	v_lshl_add_u64 v[20:21], s[0:1], 0, v[116:117]
	s_nop 0
	v_cvt_pk_bf16_f32 v16, v24, v25
	v_cvt_pk_bf16_f32 v17, v26, v27
	v_cvt_pk_bf16_f32 v18, v28, v29
	v_cvt_pk_bf16_f32 v19, v30, v31
	global_store_dwordx4 v[20:21], v[16:19], off
	v_cvt_pk_bf16_f32 v0, v0, v1
	v_cvt_pk_bf16_f32 v1, v2, v3
	v_cvt_pk_bf16_f32 v2, v4, v5
	v_cvt_pk_bf16_f32 v3, v6, v7
	v_lshl_add_u64 v[32:33], s[62:63], 0, v[112:113]
	s_nop 0
	v_mfma_f32_32x32x16_bf16 v[16:31], v[0:3], v[68:71], 0
	v_cvt_pk_bf16_f32 v0, v8, v9
	v_cvt_pk_bf16_f32 v1, v10, v11
	v_cvt_pk_bf16_f32 v2, v12, v13
	v_cvt_pk_bf16_f32 v3, v14, v15
	s_nop 1
	v_mfma_f32_32x32x16_bf16 v[16:31], v[0:3], v[64:67], v[16:31]
	s_nop 11
	v_cvt_pk_bf16_f32 v0, v16, v17
	v_cvt_pk_bf16_f32 v1, v18, v19
	v_cvt_pk_bf16_f32 v2, v20, v21
	v_cvt_pk_bf16_f32 v3, v22, v23
	global_store_dwordx4 v[32:33], v[0:3], off
	s_nop 1
	v_cvt_pk_bf16_f32 v0, v24, v25
	v_cvt_pk_bf16_f32 v1, v26, v27
	v_cvt_pk_bf16_f32 v2, v28, v29
	v_cvt_pk_bf16_f32 v3, v30, v31
	global_store_dwordx4 v[32:33], v[0:3], off offset:1024
	global_load_dwordx4 v[16:19], v[110:111], off offset:2048
	global_load_dwordx4 v[20:23], v[110:111], off offset:3072
	s_waitcnt vmcnt(1)
	v_mfma_f32_32x32x16_bf16 v[0:15], v[16:19], v[48:51], 0
	s_waitcnt vmcnt(0)
	v_mfma_f32_32x32x16_bf16 v[0:15], v[20:23], v[56:59], v[0:15]
	s_nop 11
	v_cvt_pk_bf16_f32 v0, v0, v1
	v_cvt_pk_bf16_f32 v1, v2, v3
	v_cvt_pk_bf16_f32 v2, v4, v5
	v_cvt_pk_bf16_f32 v3, v6, v7
	v_lshl_add_u64 v[4:5], s[2:3], 0, v[120:121]
	global_store_dwordx4 v[4:5], v[0:3], off
	v_lshl_add_u64 v[4:5], s[2:3], 0, v[124:125]
	s_nop 0
	v_cvt_pk_bf16_f32 v0, v8, v9
	v_cvt_pk_bf16_f32 v1, v10, v11
	v_cvt_pk_bf16_f32 v2, v12, v13
	v_cvt_pk_bf16_f32 v3, v14, v15
	global_store_dwordx4 v[4:5], v[0:3], off
	global_load_dwordx4 v[0:3], v[128:129], off
	s_nop 0
	global_load_dwordx4 v[24:27], v[130:131], off
	s_waitcnt vmcnt(1)
	v_mfma_f32_32x32x16_bf16 v[0:15], v[68:71], v[0:3], 0
	s_waitcnt vmcnt(0)
	v_mfma_f32_32x32x16_bf16 v[0:15], v[64:67], v[24:27], v[0:15]
	v_mfma_f32_32x32x16_bf16 v[0:15], v[42:45], v[16:19], v[0:15]
	v_mfma_f32_32x32x16_bf16 v[0:15], v[52:55], v[20:23], v[0:15]
	global_load_dwordx4 v[16:19], v[62:63], off
	global_load_dwordx4 v[42:45], v[60:61], off
	s_waitcnt vmcnt(1)
	v_mfma_f32_32x32x16_bf16 v[16:31], v[68:71], v[16:19], 0
	s_waitcnt vmcnt(0)
	v_mfma_f32_32x32x16_bf16 v[16:31], v[64:67], v[42:45], v[16:31]
	global_load_dwordx4 v[42:45], v[122:123], off
	s_waitcnt vmcnt(0)
	v_mfma_f32_32x32x16_bf16 v[16:31], v[38:41], v[42:45], v[16:31]
	global_load_dwordx4 v[38:41], v[126:127], off
	s_waitcnt vmcnt(0)
	v_mfma_f32_32x32x16_bf16 v[16:31], v[34:37], v[38:41], v[16:31]
	s_nop 11
	v_cvt_pk_bf16_f32 v16, v16, v17
	v_cvt_pk_bf16_f32 v17, v18, v19
	v_cvt_pk_bf16_f32 v18, v20, v21
	v_cvt_pk_bf16_f32 v19, v22, v23
	v_lshl_add_u64 v[20:21], s[0:1], 0, v[120:121]
	global_store_dwordx4 v[20:21], v[16:19], off
	v_lshl_add_u64 v[20:21], s[0:1], 0, v[124:125]
	s_nop 0
	v_cvt_pk_bf16_f32 v16, v24, v25
	v_cvt_pk_bf16_f32 v17, v26, v27
	v_cvt_pk_bf16_f32 v18, v28, v29
	v_cvt_pk_bf16_f32 v19, v30, v31
	global_store_dwordx4 v[20:21], v[16:19], off
	v_cvt_pk_bf16_f32 v0, v0, v1
	v_cvt_pk_bf16_f32 v1, v2, v3
	v_cvt_pk_bf16_f32 v2, v4, v5
	v_cvt_pk_bf16_f32 v3, v6, v7
	v_readlane_b32 s0, v255, 42
	s_add_i32 s66, s66, s0
	v_mfma_f32_32x32x16_bf16 v[16:31], v[0:3], v[68:71], 0
	v_cvt_pk_bf16_f32 v0, v8, v9
	v_cvt_pk_bf16_f32 v1, v10, v11
	v_cvt_pk_bf16_f32 v2, v12, v13
	v_cvt_pk_bf16_f32 v3, v14, v15
	s_cmpk_lt_i32 s66, 0x820
	s_nop 0
	v_mfma_f32_32x32x16_bf16 v[16:31], v[0:3], v[64:67], v[16:31]
	s_nop 11
	v_cvt_pk_bf16_f32 v0, v16, v17
	v_cvt_pk_bf16_f32 v1, v18, v19
	v_cvt_pk_bf16_f32 v2, v20, v21
	v_cvt_pk_bf16_f32 v3, v22, v23
	global_store_dwordx4 v[32:33], v[0:3], off offset:2048
	s_nop 1
	v_cvt_pk_bf16_f32 v0, v24, v25
	v_cvt_pk_bf16_f32 v1, v26, v27
	v_cvt_pk_bf16_f32 v2, v28, v29
	v_cvt_pk_bf16_f32 v3, v30, v31
	global_store_dwordx4 v[32:33], v[0:3], off offset:3072
	s_waitcnt lgkmcnt(0)
	s_cbranch_scc0 .LBB0_1027

.LBB0_995:
	s_or_b64 exec, exec, s[0:1]
	s_mov_b64 s[0:1], 0x1000
	v_lshl_add_u64 v[0:1], v[110:111], 0, s[0:1]
	s_mov_b64 s[0:1], 0x1400
	v_lshl_add_u64 v[16:17], v[110:111], 0, s[0:1]
	s_mov_b64 s[0:1], 0x2400
	v_lshl_add_u64 v[26:27], v[110:111], 0, s[0:1]
	s_mov_b64 s[0:1], 0x3400
	v_lshl_add_u64 v[134:135], v[110:111], 0, s[0:1]
	s_mov_b64 s[0:1], 0x1800
	v_lshl_add_u64 v[30:31], v[110:111], 0, s[0:1]
	s_mov_b64 s[0:1], 0x2800
	v_lshl_add_u64 v[22:23], v[110:111], 0, s[0:1]
	s_mov_b64 s[0:1], 0x3800
	v_lshl_add_u64 v[128:129], v[110:111], 0, s[0:1]
	s_mov_b64 s[0:1], 0x1c00
	v_lshl_add_u64 v[28:29], v[110:111], 0, s[0:1]
	s_mov_b64 s[0:1], 0x2c00
	s_waitcnt vmcnt(0)
	v_add_u32_e32 v141, 8, v108
	v_lshl_add_u64 v[20:21], v[110:111], 0, s[0:1]
	s_mov_b64 s[0:1], 0x3c00
	v_add_u32_e32 v140, 16, v108
	v_add_u32_e32 v142, 9, v108
	v_lshl_add_u64 v[24:25], v[110:111], 0, s[68:69]
	v_lshl_add_u64 v[132:133], v[110:111], 0, s[80:81]
	v_add_u32_e32 v139, 17, v108
	v_lshl_add_u64 v[130:131], v[110:111], 0, s[0:1]
	v_or_b32_e32 v2, 2, v141
	v_or_b32_e32 v3, 3, v141
	v_add_u32_e32 v143, 24, v108
	v_add_u32_e32 v144, 19, v108
	v_add_u32_e32 v145, 18, v108
	v_or_b32_e32 v149, 2, v108
	v_or_b32_e32 v148, 3, v108
	v_add_u32_e32 v147, 10, v108
	v_add_u32_e32 v146, 11, v108
	v_cmp_eq_u32_e32 vcc, v108, v107
	v_add_u32_e32 v150, 25, v108
	v_add_u32_e32 v151, 26, v108
	v_cndmask_b32_e64 v4, 0, 1.0, vcc
	v_cmp_eq_u32_e32 vcc, v140, v107
	v_add_u32_e32 v152, 27, v108
	s_nop 0
	v_cndmask_b32_e64 v5, 0, 1.0, vcc
	v_cmp_eq_u32_e32 vcc, v109, v107
	s_nop 1
	v_cndmask_b32_e64 v6, 0, 1.0, vcc
	v_cmp_eq_u32_e32 vcc, v139, v107
	v_cvt_pk_bf16_f32 v68, v4, v6
	s_nop 0
	v_cndmask_b32_e64 v7, 0, 1.0, vcc
	v_cmp_eq_u32_e32 vcc, v149, v107
	v_cvt_pk_bf16_f32 v64, v5, v7
	s_nop 0
	v_cndmask_b32_e64 v8, 0, 1.0, vcc
	v_cmp_eq_u32_e32 vcc, v145, v107
	s_nop 1
	v_cndmask_b32_e64 v9, 0, 1.0, vcc
	v_cmp_eq_u32_e32 vcc, v148, v107
	s_nop 1
	v_cndmask_b32_e64 v10, 0, 1.0, vcc
	v_cmp_eq_u32_e32 vcc, v144, v107
	v_cvt_pk_bf16_f32 v69, v8, v10
	s_nop 0
	v_cndmask_b32_e64 v11, 0, 1.0, vcc
	v_cmp_eq_u32_e32 vcc, v141, v107
	v_cvt_pk_bf16_f32 v65, v9, v11
	s_nop 0
	v_cndmask_b32_e64 v12, 0, 1.0, vcc
	v_cmp_eq_u32_e32 vcc, v143, v107
	s_nop 1
	v_cndmask_b32_e64 v13, 0, 1.0, vcc
	v_cmp_eq_u32_e32 vcc, v142, v107
	s_nop 1
	v_cndmask_b32_e64 v14, 0, 1.0, vcc
	v_cmp_eq_u32_e32 vcc, v150, v107
	v_cvt_pk_bf16_f32 v70, v12, v14
	s_nop 0
	v_cndmask_b32_e64 v15, 0, 1.0, vcc
	v_cmp_eq_u32_e32 vcc, v2, v107
	v_cvt_pk_bf16_f32 v66, v13, v15
	s_nop 0
	v_cndmask_b32_e64 v2, 0, 1.0, vcc
	v_cmp_eq_u32_e32 vcc, v151, v107
	s_nop 1
	v_cndmask_b32_e64 v18, 0, 1.0, vcc
	v_cmp_eq_u32_e32 vcc, v3, v107
	s_nop 1
	v_cndmask_b32_e64 v3, 0, 1.0, vcc
	v_cvt_pk_bf16_f32 v71, v2, v3
	global_load_dwordx4 v[0:3], v[0:1], off
	v_cmp_eq_u32_e32 vcc, v152, v107
	s_nop 1
	v_cndmask_b32_e64 v19, 0, 1.0, vcc
	v_cvt_pk_bf16_f32 v67, v18, v19
	global_load_dwordx4 v[16:19], v[16:17], off
	s_waitcnt vmcnt(1)
	v_mfma_f32_32x32x16_bf16 v[0:15], v[0:3], v[68:71], 0
	s_waitcnt vmcnt(0)
	v_mfma_f32_32x32x16_bf16 v[0:15], v[16:19], v[64:67], v[0:15]
	s_nop 11
	v_cvt_pk_bf16_f32 v16, v0, v1
	v_cvt_pk_bf16_f32 v17, v2, v3
	global_load_dwordx4 v[0:3], v[30:31], off
	v_cvt_pk_bf16_f32 v18, v4, v5
	global_load_dwordx4 v[28:31], v[28:29], off
	v_cvt_pk_bf16_f32 v19, v6, v7
	v_cvt_pk_bf16_f32 v72, v8, v9
	v_cvt_pk_bf16_f32 v73, v10, v11
	v_cvt_pk_bf16_f32 v74, v12, v13
	v_cvt_pk_bf16_f32 v75, v14, v15
	s_waitcnt vmcnt(1)
	v_mfma_f32_32x32x16_bf16 v[0:15], v[0:3], v[68:71], 0
	s_waitcnt vmcnt(0)
	v_mfma_f32_32x32x16_bf16 v[0:15], v[28:31], v[64:67], v[0:15]
	s_nop 11
	v_cvt_pk_bf16_f32 v76, v8, v9
	v_cvt_pk_bf16_f32 v77, v10, v11
	v_cvt_pk_bf16_f32 v78, v12, v13
	v_cvt_pk_bf16_f32 v79, v14, v15
	v_cvt_pk_bf16_f32 v80, v0, v1
	v_cvt_pk_bf16_f32 v81, v2, v3
	v_cvt_pk_bf16_f32 v82, v4, v5
	v_cvt_pk_bf16_f32 v83, v6, v7
	global_load_dwordx4 v[0:3], v[110:111], off
	global_load_dwordx4 v[28:31], v[110:111], off offset:1024
	s_waitcnt vmcnt(1)
	v_mfma_f32_32x32x16_bf16 v[0:15], v[0:3], v[68:71], 0
	s_waitcnt vmcnt(0)
	v_mfma_f32_32x32x16_bf16 v[0:15], v[28:31], v[64:67], v[0:15]
	global_load_dwordx4 v[28:31], v[110:111], off offset:3072
	s_nop 10
	v_cvt_pk_bf16_f32 v32, v0, v1
	v_cvt_pk_bf16_f32 v33, v2, v3
	global_load_dwordx4 v[0:3], v[110:111], off offset:2048
	v_cvt_pk_bf16_f32 v34, v4, v5
	v_cvt_pk_bf16_f32 v35, v6, v7
	v_cvt_pk_bf16_f32 v84, v8, v9
	v_cvt_pk_bf16_f32 v85, v10, v11
	v_cvt_pk_bf16_f32 v86, v12, v13
	v_cvt_pk_bf16_f32 v87, v14, v15
	s_waitcnt vmcnt(0)
	v_mfma_f32_32x32x16_bf16 v[0:15], v[0:3], v[68:71], 0
	v_mfma_f32_32x32x16_bf16 v[0:15], v[28:31], v[64:67], v[0:15]
	s_nop 11
	v_cvt_pk_bf16_f32 v92, v0, v1
	v_cvt_pk_bf16_f32 v93, v2, v3
	v_cvt_pk_bf16_f32 v94, v4, v5
	v_cvt_pk_bf16_f32 v95, v6, v7
	v_cvt_pk_bf16_f32 v88, v8, v9
	v_cvt_pk_bf16_f32 v89, v10, v11
	v_cvt_pk_bf16_f32 v90, v12, v13
	v_cvt_pk_bf16_f32 v91, v14, v15
	global_load_dwordx4 v[0:3], v[24:25], off
	s_waitcnt vmcnt(0)
	v_mfma_f32_32x32x16_bf16 v[0:15], v[0:3], v[68:71], 0
	global_load_dwordx4 v[24:27], v[26:27], off
	s_waitcnt vmcnt(0)
	v_mfma_f32_32x32x16_bf16 v[0:15], v[24:27], v[64:67], v[0:15]
	s_nop 11
	v_cvt_pk_bf16_f32 v102, v0, v1
	v_cvt_pk_bf16_f32 v103, v2, v3
	global_load_dwordx4 v[0:3], v[22:23], off
	v_cvt_pk_bf16_f32 v104, v4, v5
	global_load_dwordx4 v[20:23], v[20:21], off
	v_cvt_pk_bf16_f32 v105, v6, v7
	v_cvt_pk_bf16_f32 v98, v8, v9
	v_cvt_pk_bf16_f32 v99, v10, v11
	v_cvt_pk_bf16_f32 v100, v12, v13
	v_cvt_pk_bf16_f32 v101, v14, v15
	s_waitcnt vmcnt(1)
	v_mfma_f32_32x32x16_bf16 v[0:15], v[0:3], v[68:71], 0
	s_waitcnt vmcnt(0)
	v_mfma_f32_32x32x16_bf16 v[0:15], v[20:23], v[64:67], v[0:15]
	s_nop 11
	v_cvt_pk_bf16_f32 v154, v0, v1
	v_cvt_pk_bf16_f32 v155, v2, v3
	v_cvt_pk_bf16_f32 v156, v4, v5
	v_cvt_pk_bf16_f32 v157, v6, v7
	v_cvt_pk_bf16_f32 v158, v8, v9
	v_cvt_pk_bf16_f32 v159, v10, v11
	v_cvt_pk_bf16_f32 v160, v12, v13
	v_cvt_pk_bf16_f32 v161, v14, v15
	global_load_dwordx4 v[0:3], v[132:133], off
	global_load_dwordx4 v[20:23], v[134:135], off
	s_waitcnt vmcnt(1)
	v_mfma_f32_32x32x16_bf16 v[0:15], v[0:3], v[68:71], 0
	s_waitcnt vmcnt(0)
	v_mfma_f32_32x32x16_bf16 v[0:15], v[20:23], v[64:67], v[0:15]
	global_load_dwordx4 v[20:23], v[130:131], off
	s_nop 10
	v_cvt_pk_bf16_f32 v162, v0, v1
	v_cvt_pk_bf16_f32 v163, v2, v3
	global_load_dwordx4 v[0:3], v[128:129], off
	v_cvt_pk_bf16_f32 v164, v4, v5
	v_cvt_pk_bf16_f32 v165, v6, v7
	v_cvt_pk_bf16_f32 v166, v8, v9
	v_cvt_pk_bf16_f32 v167, v10, v11
	v_cvt_pk_bf16_f32 v168, v12, v13
	v_cvt_pk_bf16_f32 v169, v14, v15
	s_waitcnt vmcnt(0)
	v_mfma_f32_32x32x16_bf16 v[0:15], v[0:3], v[68:71], 0
	v_mfma_f32_32x32x16_bf16 v[0:15], v[20:23], v[64:67], v[0:15]
	s_nop 11
	v_cvt_pk_bf16_f32 v170, v0, v1
	v_cvt_pk_bf16_f32 v171, v2, v3
	v_cvt_pk_bf16_f32 v172, v4, v5
	v_cvt_pk_bf16_f32 v173, v6, v7
	v_cvt_pk_bf16_f32 v174, v8, v9
	v_cvt_pk_bf16_f32 v175, v10, v11
	v_cvt_pk_bf16_f32 v176, v12, v13
	v_cvt_pk_bf16_f32 v177, v14, v15
	v_mfma_f32_32x32x16_bf16 v[48:63], v[16:19], v[32:35], 0
	s_movk_i32 s0, 0x210
	v_cmp_lt_i32_e32 vcc, v108, v107
	s_movk_i32 s2, 0x84
	v_mfma_f32_32x32x16_bf16 v[48:63], v[72:75], v[84:87], v[48:63]
	v_mfma_f32_32x32x16_bf16 v[48:63], v[80:83], v[92:95], v[48:63]
	v_mfma_f32_32x32x16_bf16 v[16:31], v[16:19], v[162:165], 0
	v_mfma_f32_32x32x16_bf16 v[32:47], v[32:35], v[102:105], 0
	v_mfma_f32_32x32x16_bf16 v[0:15], v[102:105], v[162:165], 0
	v_mfma_f32_32x32x16_bf16 v[48:63], v[76:79], v[88:91], v[48:63]
	v_mfma_f32_32x32x16_bf16 v[16:31], v[72:75], v[166:169], v[16:31]
	v_lshl_add_u32 v72, v107, 2, s76
	v_mul_lo_u32 v73, v138, s0
	s_nop 8
	v_cndmask_b32_e32 v48, 0, v48, vcc
	v_cmp_lt_i32_e64 s[0:1], v109, v107
	v_mfma_f32_32x32x16_bf16 v[32:47], v[84:87], v[98:101], v[32:47]
	v_add_u32_e32 v84, v72, v73
	ds_write_b32 v84, v48
	v_cndmask_b32_e64 v48, 0, v49, s[0:1]
	v_mul_lo_u32 v49, v109, s2
	v_cmp_lt_i32_e64 s[0:1], v149, v107
	v_add_u32_e32 v73, v72, v49
	v_add_u32_e32 v49, 0x4a4, v49
	v_mfma_f32_32x32x16_bf16 v[0:15], v[98:101], v[166:169], v[0:15]
	v_cndmask_b32_e64 v50, 0, v50, s[0:1]
	v_cmp_lt_i32_e64 s[0:1], v148, v107
	ds_write2_b32 v73, v48, v50 offset1:33
	s_nop 0
	v_cndmask_b32_e64 v48, 0, v51, s[0:1]
	v_cmp_lt_i32_e64 s[0:1], v141, v107
	v_mfma_f32_32x32x16_bf16 v[16:31], v[80:83], v[170:173], v[16:31]
	s_nop 0
	v_cndmask_b32_e64 v50, 0, v52, s[0:1]
	v_cmp_lt_i32_e64 s[0:1], v142, v107
	ds_write2_b32 v73, v48, v50 offset0:66 offset1:231
	v_add_u32_e32 v52, v72, v49
	v_cndmask_b32_e64 v48, 0, v53, s[0:1]
	v_cmp_lt_i32_e64 s[0:1], v147, v107
	ds_write_b32 v73, v48 offset:1056
	v_mfma_f32_32x32x16_bf16 v[32:47], v[92:95], v[154:157], v[32:47]
	v_cndmask_b32_e64 v48, 0, v54, s[0:1]
	v_cmp_lt_i32_e64 s[0:1], v146, v107
	v_add_u32_e32 v50, 0x400, v52
	s_nop 0
	v_cndmask_b32_e64 v49, 0, v55, s[0:1]
	v_cmp_lt_i32_e64 s[0:1], v140, v107
	ds_write2_b32 v52, v48, v49 offset1:33
	v_mfma_f32_32x32x16_bf16 v[0:15], v[154:157], v[170:173], v[0:15]
	v_cndmask_b32_e64 v48, 0, v56, s[0:1]
	v_cmp_lt_i32_e64 s[0:1], v139, v107
	s_nop 1
	v_cndmask_b32_e64 v49, 0, v57, s[0:1]
	v_cmp_lt_i32_e64 s[0:1], v145, v107
	ds_write2_b32 v52, v48, v49 offset0:198 offset1:231
	v_mfma_f32_32x32x16_bf16 v[16:31], v[76:79], v[174:177], v[16:31]
	v_cndmask_b32_e64 v48, 0, v58, s[0:1]
	v_cmp_lt_i32_e64 s[0:1], v144, v107
	s_nop 1
	v_cndmask_b32_e64 v49, 0, v59, s[0:1]
	v_cmp_lt_i32_e64 s[0:1], v143, v107
	ds_write2_b32 v50, v48, v49 offset0:8 offset1:41
	v_mfma_f32_32x32x16_bf16 v[32:47], v[88:91], v[158:161], v[32:47]
	v_cndmask_b32_e64 v48, 0, v60, s[0:1]
	v_cmp_lt_i32_e64 s[0:1], v150, v107
	s_nop 1
	v_cndmask_b32_e64 v49, 0, v61, s[0:1]
	v_cmp_lt_i32_e64 s[0:1], v151, v107
	ds_write2_b32 v50, v48, v49 offset0:206 offset1:239
	v_mfma_f32_32x32x16_bf16 v[0:15], v[158:161], v[174:177], v[0:15]
	v_cndmask_b32_e64 v48, 0, v62, s[0:1]
	v_cmp_lt_i32_e64 s[0:1], v152, v107
	v_add_u32_e32 v50, 0x800, v52
	s_nop 0
	v_cndmask_b32_e64 v49, 0, v63, s[0:1]
	ds_write2_b32 v50, v48, v49 offset0:16 offset1:49
	s_waitcnt lgkmcnt(0)
	v_and_b32_e32 v56, 16, v136
	v_lshl_add_u32 v58, v56, 2, s76
	v_mad_u32_u24 v61, v56, s2, v58
	v_and_b32_e32 v55, 15, v136
	v_lshl_add_u32 v58, v55, 2, v58
	v_mul_u32_u24_e32 v57, 0x84, v56
	ds_read_b32 v187, v61 offset:1908
	ds_read_b32 v192, v61 offset:1772
	ds_read_b32 v193, v61 offset:1776
	ds_read_b32 v194, v61 offset:1636
	ds_read_b32 v195, v61 offset:1640
	ds_read_b32 v196, v61 offset:1644
	ds_read_b32 v197, v61 offset:1500
	ds_read_b32 v198, v61 offset:1504
	ds_read_b32 v199, v61 offset:1508
	ds_read_b32 v200, v61 offset:1512
	ds_read_b32 v201, v61 offset:1364
	ds_read_b32 v202, v61 offset:1368
	ds_read_b32 v203, v61 offset:1372
	ds_read_b32 v204, v61 offset:1376
	ds_read_b32 v205, v61 offset:1380
	ds_read_b32 v206, v61 offset:1228
	ds_read_b32 v207, v61 offset:1232
	ds_read_b32 v208, v61 offset:1236
	ds_read_b32 v209, v61 offset:1240
	ds_read_b32 v210, v61 offset:1244
	ds_read_b32 v211, v61 offset:1248
	ds_read_b32 v212, v61 offset:1092
	ds_read_b32 v213, v61 offset:1096
	ds_read_b32 v222, v61 offset:1100
	ds_read_b32 v223, v61 offset:1104
	ds_read_b32 v224, v61 offset:1108
	ds_read_b32 v225, v61 offset:1112
	ds_read_b32 v226, v61 offset:1116
	v_cmp_eq_u32_e64 s[0:1], 15, v55
	s_nop 1
	v_cndmask_b32_e64 v50, 0, 1.0, s[0:1]
	v_cmp_eq_u32_e64 s[0:1], 14, v55
	s_nop 1
	v_cndmask_b32_e64 v51, 0, 1.0, s[0:1]
	v_cmp_eq_u32_e64 s[0:1], 13, v55
	s_nop 1
	v_cndmask_b32_e64 v53, 0, 1.0, s[0:1]
	v_cmp_eq_u32_e64 s[0:1], 12, v55
	s_nop 1
	v_cndmask_b32_e64 v54, 0, 1.0, s[0:1]
	v_cmp_eq_u32_e64 s[0:1], 11, v55
	s_nop 1
	v_cndmask_b32_e64 v59, 0, 1.0, s[0:1]
	v_cmp_eq_u32_e64 s[0:1], 10, v55
	s_nop 1
	v_cndmask_b32_e64 v60, 0, 1.0, s[0:1]
	v_cmp_eq_u32_e64 s[0:1], 9, v55
	s_nop 1
	v_cndmask_b32_e64 v62, 0, 1.0, s[0:1]
	v_cmp_eq_u32_e64 s[0:1], 8, v55
	s_nop 1
	v_cndmask_b32_e64 v63, 0, 1.0, s[0:1]
	v_cmp_eq_u32_e64 s[0:1], 7, v55
	s_nop 1
	v_cndmask_b32_e64 v74, 0, 1.0, s[0:1]
	v_cmp_eq_u32_e64 s[0:1], 6, v55
	s_nop 1
	v_cndmask_b32_e64 v75, 0, 1.0, s[0:1]
	v_cmp_eq_u32_e64 s[0:1], 5, v55
	s_nop 1
	v_cndmask_b32_e64 v76, 0, 1.0, s[0:1]
	v_cmp_eq_u32_e64 s[0:1], 4, v55
	s_nop 1
	v_cndmask_b32_e64 v77, 0, 1.0, s[0:1]
	v_cmp_eq_u32_e64 s[0:1], 3, v55
	s_nop 1
	v_cndmask_b32_e64 v78, 0, 1.0, s[0:1]
	v_cmp_eq_u32_e64 s[0:1], 2, v55
	s_nop 1
	v_cndmask_b32_e64 v49, 0, 1.0, s[0:1]
	v_cmp_eq_u32_e64 s[0:1], 1, v55
	s_nop 1
	v_cndmask_b32_e64 v79, 0, 1.0, s[0:1]
	v_cmp_eq_u32_e64 s[0:1], 0, v55
	s_nop 1
	v_cndmask_b32_e64 v48, 0, 1.0, s[0:1]
	s_waitcnt lgkmcnt(0)
	v_fma_f32 v51, -v187, v50, v51
	v_fma_f32 v53, -v192, v51, v53
	v_fma_f32 v53, -v193, v50, v53
	v_fma_f32 v54, -v194, v53, v54
	v_fma_f32 v54, -v195, v51, v54
	v_fma_f32 v54, -v196, v50, v54
	v_fma_f32 v59, -v197, v54, v59
	v_fma_f32 v59, -v198, v53, v59
	v_fma_f32 v59, -v199, v51, v59
	v_fma_f32 v59, -v200, v50, v59
	v_fma_f32 v60, -v201, v59, v60
	v_fma_f32 v60, -v202, v54, v60
	v_fma_f32 v60, -v203, v53, v60
	v_fma_f32 v60, -v204, v51, v60
	v_fma_f32 v60, -v205, v50, v60
	v_fma_f32 v62, -v206, v60, v62
	v_fma_f32 v62, -v207, v59, v62
	v_fma_f32 v62, -v208, v54, v62
	v_fma_f32 v62, -v209, v53, v62
	v_fma_f32 v62, -v210, v51, v62
	v_fma_f32 v62, -v211, v50, v62
	v_fma_f32 v63, -v212, v62, v63
	v_fma_f32 v63, -v213, v60, v63
	v_fma_f32 v63, -v222, v59, v63
	v_fma_f32 v63, -v223, v54, v63
	v_fma_f32 v63, -v224, v53, v63
	v_fma_f32 v63, -v225, v51, v63
	v_fma_f32 v63, -v226, v50, v63
	ds_read_b32 v187, v61 offset:956
	ds_read_b32 v192, v61 offset:960
	ds_read_b32 v193, v61 offset:964
	ds_read_b32 v194, v61 offset:968
	ds_read_b32 v195, v61 offset:972
	ds_read_b32 v196, v61 offset:976
	ds_read_b32 v197, v61 offset:980
	ds_read_b32 v198, v61 offset:984
	ds_read_b32 v199, v61 offset:820
	ds_read_b32 v200, v61 offset:824
	ds_read_b32 v201, v61 offset:828
	ds_read_b32 v202, v61 offset:832
	ds_read_b32 v203, v61 offset:836
	ds_read_b32 v204, v61 offset:840
	ds_read_b32 v205, v61 offset:844
	ds_read_b32 v206, v61 offset:848
	ds_read_b32 v207, v61 offset:852
	ds_read_b32 v208, v61 offset:684
	ds_read_b32 v209, v61 offset:688
	ds_read_b32 v210, v61 offset:692
	ds_read_b32 v211, v61 offset:696
	ds_read_b32 v212, v61 offset:700
	ds_read_b32 v213, v61 offset:704
	ds_read_b32 v222, v61 offset:708
	ds_read_b32 v223, v61 offset:712
	ds_read_b32 v224, v61 offset:716
	ds_read_b32 v225, v61 offset:720
	s_waitcnt lgkmcnt(0)
	v_fma_f32 v74, -v187, v63, v74
	v_fma_f32 v74, -v192, v62, v74
	v_fma_f32 v74, -v193, v60, v74
	v_fma_f32 v74, -v194, v59, v74
	v_fma_f32 v74, -v195, v54, v74
	v_fma_f32 v74, -v196, v53, v74
	v_fma_f32 v74, -v197, v51, v74
	v_fma_f32 v74, -v198, v50, v74
	v_fma_f32 v75, -v199, v74, v75
	v_fma_f32 v75, -v200, v63, v75
	v_fma_f32 v75, -v201, v62, v75
	v_fma_f32 v75, -v202, v60, v75
	v_fma_f32 v75, -v203, v59, v75
	v_fma_f32 v75, -v204, v54, v75
	v_fma_f32 v75, -v205, v53, v75
	v_fma_f32 v75, -v206, v51, v75
	v_fma_f32 v75, -v207, v50, v75
	v_fma_f32 v76, -v208, v75, v76
	v_fma_f32 v76, -v209, v74, v76
	v_fma_f32 v76, -v210, v63, v76
	v_fma_f32 v76, -v211, v62, v76
	v_fma_f32 v76, -v212, v60, v76
	v_fma_f32 v76, -v213, v59, v76
	v_fma_f32 v76, -v222, v54, v76
	v_fma_f32 v76, -v223, v53, v76
	v_fma_f32 v76, -v224, v51, v76
	v_fma_f32 v76, -v225, v50, v76
	ds_read_b32 v187, v61 offset:548
	ds_read_b32 v192, v61 offset:552
	ds_read_b32 v193, v61 offset:556
	ds_read_b32 v194, v61 offset:560
	ds_read_b32 v195, v61 offset:564
	ds_read_b32 v196, v61 offset:568
	ds_read_b32 v197, v61 offset:572
	ds_read_b32 v198, v61 offset:576
	ds_read_b32 v199, v61 offset:580
	ds_read_b32 v200, v61 offset:584
	ds_read_b32 v201, v61 offset:588
	ds_read_b32 v202, v61 offset:412
	ds_read_b32 v203, v61 offset:416
	ds_read_b32 v204, v61 offset:420
	ds_read_b32 v205, v61 offset:424
	ds_read_b32 v206, v61 offset:428
	ds_read_b32 v207, v61 offset:432
	ds_read_b32 v208, v61 offset:436
	ds_read_b32 v209, v61 offset:440
	ds_read_b32 v210, v61 offset:444
	ds_read_b32 v211, v61 offset:448
	ds_read_b32 v212, v61 offset:452
	ds_read_b32 v213, v61 offset:456
	ds_read_b32 v222, v61 offset:276
	ds_read_b32 v223, v61 offset:280
	ds_read_b32 v224, v61 offset:284
	ds_read_b32 v225, v61 offset:288
	ds_read_b32 v226, v61 offset:292
	ds_read_b32 v227, v61 offset:296
	ds_read_b32 v228, v61 offset:300
	ds_read_b32 v229, v61 offset:304
	ds_read_b32 v233, v61 offset:308
	ds_read_b32 v234, v61 offset:312
	ds_read_b32 v235, v61 offset:316
	ds_read_b32 v236, v61 offset:320
	ds_read_b32 v238, v61 offset:324
	s_waitcnt lgkmcnt(0)
	v_fma_f32 v77, -v187, v76, v77
	v_fma_f32 v77, -v192, v75, v77
	v_fma_f32 v77, -v193, v74, v77
	v_fma_f32 v77, -v194, v63, v77
	v_fma_f32 v77, -v195, v62, v77
	v_fma_f32 v77, -v196, v60, v77
	v_fma_f32 v77, -v197, v59, v77
	v_fma_f32 v77, -v198, v54, v77
	v_fma_f32 v77, -v199, v53, v77
	v_fma_f32 v77, -v200, v51, v77
	v_fma_f32 v77, -v201, v50, v77
	v_fma_f32 v78, -v202, v77, v78
	v_fma_f32 v78, -v203, v76, v78
	v_fma_f32 v78, -v204, v75, v78
	v_fma_f32 v78, -v205, v74, v78
	v_fma_f32 v78, -v206, v63, v78
	v_fma_f32 v78, -v207, v62, v78
	v_fma_f32 v78, -v208, v60, v78
	v_fma_f32 v78, -v209, v59, v78
	v_fma_f32 v78, -v210, v54, v78
	v_fma_f32 v78, -v211, v53, v78
	v_fma_f32 v78, -v212, v51, v78
	v_fma_f32 v78, -v213, v50, v78
	v_fma_f32 v49, -v222, v78, v49
	v_fma_f32 v49, -v223, v77, v49
	v_fma_f32 v49, -v224, v76, v49
	v_fma_f32 v49, -v225, v75, v49
	v_fma_f32 v49, -v226, v74, v49
	v_fma_f32 v49, -v227, v63, v49
	v_fma_f32 v49, -v228, v62, v49
	v_fma_f32 v49, -v229, v60, v49
	v_fma_f32 v49, -v233, v59, v49
	v_fma_f32 v49, -v234, v54, v49
	v_fma_f32 v49, -v235, v53, v49
	v_fma_f32 v49, -v236, v51, v49
	v_fma_f32 v49, -v238, v50, v49
	ds_read_b32 v187, v61 offset:140
	ds_read_b32 v192, v61 offset:144
	ds_read_b32 v193, v61 offset:148
	ds_read_b32 v194, v61 offset:152
	ds_read_b32 v195, v61 offset:156
	ds_read_b32 v196, v61 offset:160
	ds_read_b32 v197, v61 offset:164
	ds_read_b32 v198, v61 offset:168
	ds_read_b32 v199, v61 offset:172
	ds_read_b32 v200, v61 offset:176
	ds_read_b32 v201, v61 offset:180
	ds_read_b32 v202, v61 offset:184
	ds_read_b32 v203, v61 offset:188
	ds_read_b32 v204, v61 offset:192
	ds_read_b32 v205, v61 offset:4
	ds_read_b32 v206, v61 offset:8
	ds_read_b32 v207, v61 offset:12
	ds_read_b32 v208, v61 offset:16
	ds_read_b32 v209, v61 offset:20
	ds_read_b32 v210, v61 offset:24
	ds_read_b32 v211, v61 offset:28
	ds_read_b32 v212, v61 offset:32
	ds_read_b32 v213, v61 offset:36
	ds_read_b32 v222, v61 offset:40
	ds_read_b32 v223, v61 offset:44
	ds_read_b32 v224, v61 offset:48
	ds_read_b32 v225, v61 offset:52
	ds_read_b32 v226, v61 offset:56
	ds_read_b32 v227, v61 offset:60
	s_waitcnt lgkmcnt(0)
	v_fma_f32 v79, -v187, v49, v79
	v_fma_f32 v79, -v192, v78, v79
	v_fma_f32 v79, -v193, v77, v79
	v_fma_f32 v79, -v194, v76, v79
	v_fma_f32 v79, -v195, v75, v79
	v_fma_f32 v79, -v196, v74, v79
	v_fma_f32 v79, -v197, v63, v79
	v_fma_f32 v79, -v198, v62, v79
	v_fma_f32 v79, -v199, v60, v79
	v_fma_f32 v79, -v200, v59, v79
	v_fma_f32 v79, -v201, v54, v79
	v_fma_f32 v79, -v202, v53, v79
	v_fma_f32 v79, -v203, v51, v79
	v_fma_f32 v79, -v204, v50, v79
	v_fma_f32 v48, -v205, v79, v48
	v_fma_f32 v48, -v206, v49, v48
	v_fma_f32 v48, -v207, v78, v48
	v_fma_f32 v48, -v208, v77, v48
	v_fma_f32 v48, -v209, v76, v48
	v_fma_f32 v48, -v210, v75, v48
	v_fma_f32 v48, -v211, v74, v48
	v_fma_f32 v48, -v212, v63, v48
	v_fma_f32 v48, -v213, v62, v48
	v_fma_f32 v48, -v222, v60, v48
	v_fma_f32 v48, -v223, v59, v48
	v_fma_f32 v48, -v224, v54, v48
	v_fma_f32 v48, -v225, v53, v48
	v_fma_f32 v48, -v226, v51, v48
	v_fma_f32 v48, -v227, v50, v48
	v_cmp_ne_u32_e64 s[0:1], 0, v56
	v_mad_u32_u24 v56, v56, s2, v58
	ds_write_b32 v56, v48 offset:4224
	v_add_u32_e32 v48, v58, v57
	s_and_saveexec_b64 s[2:3], s[0:1]
	s_xor_b64 s[2:3], exec, s[2:3]
	s_mov_b64 s[6:7], 0x4000
	ds_write_b32 v48, v79 offset:4356
	s_or_saveexec_b64 s[2:3], s[2:3]
	v_lshl_add_u32 v55, v55, 2, s76
	s_xor_b64 exec, exec, s[2:3]
	s_cbranch_execz .LBB0_999
	ds_write_b32 v55, v97 offset:6336
	ds_write_b32 v48, v79 offset:4356
	ds_write_b32 v55, v97 offset:6468
